# static s_setprio 1 for waves 0-3 (the other half) through the two MoBA attention phases, reset before the out-projection GEMM
# speedup vs baseline: 1.0076x; 1.0060x over previous
.LBB0_771:
	s_cmp_lt_u32 s73, 4
	s_cbranch_scc0 .Lmy_prio_a
	s_setprio 1
